# xn stores of the folded rmsnorm issued inside the second layer's weight-transpose loop (x_next kept in registers above v63), under the next tile's load latency
# baseline (speedup 1.0000x reference)
; #define LAS __attribute__((address_space(3)))
; DI int tidx() { int t = threadIdx.x; asm volatile("" : "+v"(t)); return t; }
; DI char* WS(const Params&) { return *(char* const __attribute__((address_space(4)))*)(KA() + 8 * 30); }
; #define TB(k) do { if (PROBE_T == (k)) t0 = __builtin_amdgcn_s_memrealtime(); } while (0)
; __global__ void __launch_bounds__(512, 2) fwd_megakernel(Params p) {
;   cg::grid_group grid = cg::this_grid();
;   extern __shared__ __attribute__((aligned(16))) char smraw[];
;   uint4* xb_words = (uint4*)(smraw + DYN_XB);
;   int* s_item = (int*)(smraw + DYN_XB + 16);
;   if (tidx() == 0) *xb_words = make_uint4(0u, 0u, 0u, 0u);
;   __syncthreads();
;   XcdBarrier xb = xcd_barrier_post((unsigned*)(WS(p) + O_BAR), (volatile LAS unsigned*)xb_words);
;   if (WS(p) == nullptr) grid.sync();
;   unsigned long long tacc = 0ull, t0 = 0ull;
;     ...
;   for (int l = 0; l < 2; ++l) {
;     TB(10);
;     phase0(p, l, smraw);
.LBB0_17:
	v_writelane_b32 v252, s2, 4
	s_lshl_b32 s1, s18, 1
	v_writelane_b32 v252, s1, 5
	v_writelane_b32 v252, s20, 6
	s_load_dword s1, s[20:21], 0x100
	s_mul_i32 s0, s19, s18
	v_writelane_b32 v252, s21, 7
	s_cmp_eq_u32 s12, 15
	v_mbcnt_lo_u32_b32 v0, -1, 0
	s_waitcnt lgkmcnt(0)
	s_mul_i32 s0, s0, s1
	v_writelane_b32 v252, s0, 8
	s_cselect_b64 s[0:1], -1, 0
	v_writelane_b32 v252, s0, 9
	s_cmp_eq_u32 s12, 14
	v_mov_b32_e32 v1, 0
	v_writelane_b32 v252, s1, 10
	s_cselect_b64 s[0:1], -1, 0
	v_writelane_b32 v252, s0, 11
	s_cmp_eq_u32 s12, 13
	v_mov_b32_e32 v222, 0x12a0000
	v_writelane_b32 v252, s1, 12
	s_cselect_b64 s[0:1], -1, 0
	v_writelane_b32 v252, s0, 13
	s_cmp_eq_u32 s12, 12
	v_mov_b32_e32 v223, 1
	v_writelane_b32 v252, s1, 14
	s_cselect_b64 s[0:1], -1, 0
	v_writelane_b32 v252, s0, 15
	s_cmp_eq_u32 s12, 11
	v_mov_b32_e32 v224, 0x260
	v_writelane_b32 v252, s1, 16
	s_cselect_b64 s[0:1], -1, 0
	v_writelane_b32 v252, s0, 17
	s_cmp_eq_u32 s12, 10
	v_mov_b32_e32 v225, 4
	v_writelane_b32 v252, s1, 18
	s_cselect_b64 s[0:1], -1, 0
	v_writelane_b32 v252, s0, 19
	s_cmp_eq_u32 s12, 9
	v_mov_b32_e32 v226, 3
	v_writelane_b32 v252, s1, 20
	s_cselect_b64 s[0:1], -1, 0
	v_writelane_b32 v252, s0, 21
	s_cmp_eq_u32 s12, 8
	v_mov_b32_e32 v200, 0x358637bd
	v_writelane_b32 v252, s1, 22
	s_cselect_b64 s[0:1], -1, 0
	v_writelane_b32 v252, s0, 23
	s_cmp_eq_u32 s12, 7
	v_mbcnt_hi_u32_b32 v227, -1, v0
	v_writelane_b32 v252, s1, 24
	s_cselect_b64 s[0:1], -1, 0
	v_writelane_b32 v252, s0, 25
	s_cmp_eq_u32 s12, 6
	v_mov_b64_e32 v[202:203], 0x3bf
	v_writelane_b32 v252, s1, 26
	s_cselect_b64 s[0:1], -1, 0
	v_writelane_b32 v252, s0, 27
	s_cmp_eq_u32 s12, 5
	v_mov_b64_e32 v[204:205], 0x3c0
	v_writelane_b32 v252, s1, 28
	s_cselect_b64 s[0:1], -1, 0
	v_writelane_b32 v252, s0, 29
	s_cmp_eq_u32 s12, 4
	v_mov_b32_e32 v228, 5
	v_writelane_b32 v252, s1, 30
	s_cselect_b64 s[0:1], -1, 0
	v_writelane_b32 v252, s0, 31
	s_cmp_eq_u32 s12, 3
	v_mov_b32_e32 v229, 0xf149f2ca
	v_writelane_b32 v252, s1, 32
	s_cselect_b64 s[0:1], -1, 0
	v_writelane_b32 v252, s0, 33
	s_cmp_eq_u32 s12, 2
	v_mov_b64_e32 v[206:207], 0x100
	v_writelane_b32 v252, s1, 34
	s_cselect_b64 s[0:1], -1, 0
	v_writelane_b32 v252, s0, 35
	s_cmp_eq_u32 s12, 1
	v_mov_b64_e32 v[208:209], 0xff
	v_writelane_b32 v252, s1, 36
	s_cselect_b64 s[0:1], -1, 0
	v_writelane_b32 v252, s0, 37
	s_cmp_eq_u32 s12, 0
	s_movk_i32 s87, 0x1e00
	v_writelane_b32 v252, s1, 38
	s_cselect_b64 s[0:1], -1, 0
	v_writelane_b32 v252, s0, 39
	s_mov_b32 s33, 0xefa18f08
	s_mov_b32 s4, 0
	v_writelane_b32 v252, s1, 40
	s_lshl_b32 s0, s12, 6
	v_writelane_b32 v252, s0, 41
	s_ashr_i32 s0, s18, 31
	v_writelane_b32 v252, s0, 42
	s_mov_b32 s0, s18
	v_writelane_b32 v252, s0, 43
	s_mov_b64 s[2:3], -1
	s_mov_b64 s[14:15], 0x40000
	v_writelane_b32 v252, s1, 44
	s_lshl_b32 s0, s18, 4
	v_writelane_b32 v252, s0, 45
	s_add_i32 s0, 0, 0x26000
	v_writelane_b32 v252, s0, 46
	s_add_i32 s0, 0, 0x26004
	v_writelane_b32 v252, s0, 47
	s_add_i32 s0, 0, 0x26014
	v_writelane_b32 v252, s0, 48
	s_add_i32 s0, 0, 0x26010
	s_mov_b64 s[16:17], 0x80
	s_mov_b64 s[18:19], 0x40080
	s_mov_b64 s[24:25], 0x20000
	s_mov_b64 s[26:27], 0x60000
	s_mov_b64 s[28:29], 0x20080
	s_mov_b64 s[30:31], 0x60080
	s_mov_b32 s89, 0
	v_writelane_b32 v252, s0, 49
	s_mov_b32 s92, 0
	s_branch .LBB0_20

; DI unsigned pack2(float a, float b) { fv2 v = {a, b}; return __builtin_bit_cast(unsigned, __builtin_convertvector(v, bfv2)); }
; DI float wave_sum_fast(float v) { v = fdpp_add(v, 0); v = fdpp_add(v, 1); v = fdpp_add(v, 2); v = fdpp_add(v, 3); v = xor16_sum(v); return xor32_sum(v); }
; DI void rmsnorm_rows(const float* x, const float* g, bf16_t* outb, float* outf) {
;     ...
;     for (int rr = 0; rr < 2; ++rr) {
; #pragma unroll
;       for (int i = 0; i < 4; ++i) ss[rr] += v[rr][i].x * v[rr][i].x + v[rr][i].y * v[rr][i].y + v[rr][i].z * v[rr][i].z + v[rr][i].w * v[rr][i].w;
;       ss[rr] = wave_sum_fast(ss[rr]);
;     }
; #pragma unroll
;     for (int rr = 0; rr < 2; ++rr) {
;       const int row = it * 16 + rr * 8 + w;
;       const float rs = rsqrtf(ss[rr] * (1.f / 1024.f) + 1e-6f);
; #pragma unroll
;       for (int i = 0; i < 4; ++i) {
;         const float o0 = v[rr][i].x * rs * gg[i].x, o1 = v[rr][i].y * rs * gg[i].y, o2 = v[rr][i].z * rs * gg[i].z, o3 = v[rr][i].w * rs * gg[i].w;
;         if (outf) { *(float4*)(outf + (size_t)row * 1024 + lane * 4 + 256 * i) = make_float4(o0, o1, o2, o3); }
;         else { uint2 o; o.x = pack2(o0, o1); o.y = pack2(o2, o3); *(uint2*)(outb + (size_t)row * 1024 + lane * 4 + 256 * i) = o; }
;       }
.LBB0_19:
	s_or_b64 exec, exec, s[2:3]
	v_readlane_b32 s0, v252, 50
	v_readlane_b32 s1, v252, 51
	s_mov_b32 s4, 1
	s_mov_b64 s[8:9], -1
	s_mov_b64 s[2:3], 0
	s_and_b64 vcc, exec, s[0:1]
	s_waitcnt lgkmcnt(0)
	s_barrier
	s_cbranch_vccnz .Ltramp_1087
	s_cmp_eq_u32 s92, 2
	s_cbranch_scc0 .Lfz_no2
	v_readlane_b32 s94, v252, 6
	v_readlane_b32 s95, v252, 7
	s_load_dwordx2 s[96:97], s[94:95], 0xf0
	s_load_dwordx2 s[98:99], s[94:95], 0x8
	v_lshrrev_b32_e32 v191, 6, v201
	v_lshrrev_b32_e32 v192, 2, v191
	v_and_b32_e32 v193, 3, v191
	v_and_b32_e32 v194, 15, v201
	v_bfe_u32 v195, v201, 4, 2
	v_lshlrev_b32_e32 v190, 17, v192
	v_lshl_or_b32 v190, v194, 11, v190
	v_lshl_or_b32 v190, v193, 6, v190
	v_lshl_or_b32 v190, v195, 3, v190
	v_lshlrev_b32_e32 v198, 2, v201
	v_mov_b32_e32 v161, 0x358637bd
	s_mov_b32 s93, 0x800000
	v_lshlrev_b32_e32 v199, 7, v193
	v_lshl_or_b32 v199, v195, 4, v199
	s_waitcnt lgkmcnt(0)
	s_lshl_b32 s88, s91, 10
	s_add_u32 s98, s98, 0x1000
	s_addc_u32 s99, s99, 0
	s_add_u32 s98, s98, s88
	s_addc_u32 s99, s99, 0
	global_load_dwordx4 v[162:165], v199, s[98:99]
	global_load_dwordx4 v[166:169], v199, s[98:99] offset:64
	global_load_dwordx4 v[170:173], v199, s[98:99] offset:512
	global_load_dwordx4 v[174:177], v199, s[98:99] offset:576
	s_add_u32 s100, s96, 0xaaa4500
	s_addc_u32 s101, s97, 0
	s_lshl_b32 s88, s90, 10
	s_add_u32 s100, s100, s88
	s_addc_u32 s101, s101, 0
	v_cmp_gt_u32_e32 vcc, 0x100, v201
	s_and_saveexec_b64 s[94:95], vcc
	global_load_dword v150, v198, s[100:101]
	s_add_u32 s100, s100, 0x10000
	s_addc_u32 s101, s101, 0
	global_load_dword v151, v198, s[100:101]
	s_add_u32 s100, s100, 0x10000
	s_addc_u32 s101, s101, 0
	global_load_dword v152, v198, s[100:101]
	s_add_u32 s100, s100, 0x10000
	s_addc_u32 s101, s101, 0
	global_load_dword v153, v198, s[100:101]
	s_waitcnt vmcnt(0)
	v_add_f32_e32 v150, v150, v151
	v_add_f32_e32 v150, v150, v152
	v_add_f32_e32 v150, v150, v153
	v_fmamk_f32 v160, v150, 0x3a800000, v161
	v_mul_f32_e32 v154, 0x4b800000, v160
	v_cmp_gt_f32_e32 vcc, s93, v160
	s_nop 1
	v_cndmask_b32_e32 v160, v160, v154, vcc
	v_rsq_f32_e32 v160, v160
	s_nop 0
	v_mul_f32_e32 v154, 0x45800000, v160
	v_cndmask_b32_e32 v160, v160, v154, vcc
	v_add_u32_e32 v155, 0x20000, v198
	ds_write_b32 v155, v160
	s_mov_b64 exec, s[94:95]
	s_waitcnt vmcnt(0) lgkmcnt(0)
	s_barrier
	v_lshl_or_b32 v196, v192, 6, v194
	v_lshlrev_b32_e32 v196, 2, v196
	v_add_u32_e32 v196, 0x20000, v196
	ds_read_b32 v182, v196
	ds_read_b32 v183, v196 offset:64
	ds_read_b32 v184, v196 offset:128
	ds_read_b32 v185, v196 offset:192
	ds_read_b32 v186, v196 offset:512
	ds_read_b32 v187, v196 offset:576
	ds_read_b32 v188, v196 offset:640
	ds_read_b32 v189, v196 offset:704
	s_add_u32 s100, s96, 0x12a4500
	s_addc_u32 s101, s97, 0
	s_lshl_b32 s88, s90, 19
	s_add_u32 s100, s100, s88
	s_addc_u32 s101, s101, 0
	s_lshl_b32 s88, s91, 9
	s_add_u32 s100, s100, s88
	s_addc_u32 s101, s101, 0
	s_waitcnt lgkmcnt(0)
	v_mov_b32_e32 v150, v62
	v_mov_b32_e32 v151, v63
	v_mov_b32_e32 v152, v64
	v_mov_b32_e32 v153, v65
	v_mov_b32_e32 v154, v58
	v_mov_b32_e32 v155, v59
	v_mov_b32_e32 v156, v60
	v_mov_b32_e32 v157, v61
	v_mov_b32_e32 v158, v54
	v_mov_b32_e32 v159, v55
	v_mov_b32_e32 v160, v56
	v_mov_b32_e32 v161, v57
	v_mov_b32_e32 v178, v50
	v_mov_b32_e32 v179, v51
	v_mov_b32_e32 v180, v52
	v_mov_b32_e32 v181, v53
	v_mov_b32_e32 v192, v46
	v_mov_b32_e32 v193, v47
	v_mov_b32_e32 v194, v48
	v_mov_b32_e32 v195, v49
	v_mov_b32_e32 v196, v42
	v_mov_b32_e32 v197, v43
	v_mov_b32_e32 v198, v44
	v_mov_b32_e32 v199, v45
	v_mov_b32_e32 v210, v38
	v_mov_b32_e32 v211, v39
	v_mov_b32_e32 v212, v40
	v_mov_b32_e32 v213, v41
	v_mov_b32_e32 v214, v34
	v_mov_b32_e32 v215, v35
	v_mov_b32_e32 v216, v36
	v_mov_b32_e32 v217, v37
	v_mov_b32_e32 v218, v30
	v_mov_b32_e32 v219, v31
	v_mov_b32_e32 v220, v32
	v_mov_b32_e32 v221, v33
	v_mov_b32_e32 v230, v26
	v_mov_b32_e32 v231, v27
	v_mov_b32_e32 v232, v28
	v_mov_b32_e32 v233, v29
	v_mov_b32_e32 v234, v22
	v_mov_b32_e32 v235, v23
	v_mov_b32_e32 v236, v24
	v_mov_b32_e32 v237, v25
	s_mov_b32 s97, 0

; DI unsigned pack2(float a, float b) { fv2 v = {a, b}; return __builtin_bit_cast(unsigned, __builtin_convertvector(v, bfv2)); }
; DI void rmsnorm_rows(const float* x, const float* g, bf16_t* outb, float* outf) {
;     ...
; #pragma unroll
;       for (int i = 0; i < 4; ++i) {
;         const float o0 = v[rr][i].x * rs * gg[i].x, o1 = v[rr][i].y * rs * gg[i].y, o2 = v[rr][i].z * rs * gg[i].z, o3 = v[rr][i].w * rs * gg[i].w;
;         if (outf) { *(float4*)(outf + (size_t)row * 1024 + lane * 4 + 256 * i) = make_float4(o0, o1, o2, o3); }
;         else { uint2 o; o.x = pack2(o0, o1); o.y = pack2(o2, o3); *(uint2*)(outb + (size_t)row * 1024 + lane * 4 + 256 * i) = o; }
.LBB0_139:
	s_cmp_eq_u32 s92, 2
	s_cbranch_scc0 .Lx2_done
	s_cmp_eq_u32 s97, 0
	s_cbranch_scc1 .Lx2_c0
	s_cmp_eq_u32 s97, 1
	s_cbranch_scc1 .Lx2_c1
	s_cmp_eq_u32 s97, 2
	s_cbranch_scc1 .Lx2_c2
	s_cmp_eq_u32 s97, 3
	s_cbranch_scc0 .Lx2_done
	s_branch .Lx2_c3
.Lx2_c0:
	s_add_u32 s94, s100, 0x0
	s_addc_u32 s95, s101, 0
	v_pk_mul_f32 v[126:127], v[126:127], v[182:183] op_sel_hi:[1,0]
	v_pk_mul_f32 v[128:129], v[128:129], v[182:183] op_sel_hi:[1,0]
	v_pk_mul_f32 v[126:127], v[162:163], v[126:127]
	v_pk_mul_f32 v[128:129], v[164:165], v[128:129]
	v_cvt_pk_bf16_f32 v126, v126, v127
	v_cvt_pk_bf16_f32 v127, v128, v129
	global_store_dwordx2 v190, v[126:127], s[94:95]
	v_pk_mul_f32 v[122:123], v[122:123], v[182:183] op_sel_hi:[1,0]
	v_pk_mul_f32 v[124:125], v[124:125], v[182:183] op_sel_hi:[1,0]
	v_pk_mul_f32 v[122:123], v[166:167], v[122:123]
	v_pk_mul_f32 v[124:125], v[168:169], v[124:125]
	v_cvt_pk_bf16_f32 v122, v122, v123
	v_cvt_pk_bf16_f32 v123, v124, v125
	global_store_dwordx2 v190, v[122:123], s[94:95] offset:32
	v_pk_mul_f32 v[110:111], v[110:111], v[182:183] op_sel_hi:[1,0]
	v_pk_mul_f32 v[112:113], v[112:113], v[182:183] op_sel_hi:[1,0]
	v_pk_mul_f32 v[110:111], v[170:171], v[110:111]
	v_pk_mul_f32 v[112:113], v[172:173], v[112:113]
	v_cvt_pk_bf16_f32 v110, v110, v111
	v_cvt_pk_bf16_f32 v111, v112, v113
	global_store_dwordx2 v190, v[110:111], s[94:95] offset:256
	v_pk_mul_f32 v[106:107], v[106:107], v[182:183] op_sel_hi:[1,0]
	v_pk_mul_f32 v[108:109], v[108:109], v[182:183] op_sel_hi:[1,0]
	v_pk_mul_f32 v[106:107], v[174:175], v[106:107]
	v_pk_mul_f32 v[108:109], v[176:177], v[108:109]
	v_cvt_pk_bf16_f32 v106, v106, v107
	v_cvt_pk_bf16_f32 v107, v108, v109
	global_store_dwordx2 v190, v[106:107], s[94:95] offset:288
	s_add_u32 s94, s100, 0x8000
	s_addc_u32 s95, s101, 0
	v_pk_mul_f32 v[118:119], v[118:119], v[182:183] op_sel:[0,1] op_sel_hi:[1,1]
	v_pk_mul_f32 v[120:121], v[120:121], v[182:183] op_sel:[0,1] op_sel_hi:[1,1]
	v_pk_mul_f32 v[118:119], v[162:163], v[118:119]
	v_pk_mul_f32 v[120:121], v[164:165], v[120:121]
	v_cvt_pk_bf16_f32 v118, v118, v119
	v_cvt_pk_bf16_f32 v119, v120, v121
	global_store_dwordx2 v190, v[118:119], s[94:95]
	v_pk_mul_f32 v[114:115], v[114:115], v[182:183] op_sel:[0,1] op_sel_hi:[1,1]
	v_pk_mul_f32 v[116:117], v[116:117], v[182:183] op_sel:[0,1] op_sel_hi:[1,1]
	v_pk_mul_f32 v[114:115], v[166:167], v[114:115]
	v_pk_mul_f32 v[116:117], v[168:169], v[116:117]
	v_cvt_pk_bf16_f32 v114, v114, v115
	v_cvt_pk_bf16_f32 v115, v116, v117
	global_store_dwordx2 v190, v[114:115], s[94:95] offset:32
	v_pk_mul_f32 v[102:103], v[102:103], v[182:183] op_sel:[0,1] op_sel_hi:[1,1]
	v_pk_mul_f32 v[104:105], v[104:105], v[182:183] op_sel:[0,1] op_sel_hi:[1,1]
	v_pk_mul_f32 v[102:103], v[170:171], v[102:103]
	v_pk_mul_f32 v[104:105], v[172:173], v[104:105]
	v_cvt_pk_bf16_f32 v102, v102, v103
	v_cvt_pk_bf16_f32 v103, v104, v105
	global_store_dwordx2 v190, v[102:103], s[94:95] offset:256
	v_pk_mul_f32 v[98:99], v[98:99], v[182:183] op_sel:[0,1] op_sel_hi:[1,1]
	v_pk_mul_f32 v[100:101], v[100:101], v[182:183] op_sel:[0,1] op_sel_hi:[1,1]
	v_pk_mul_f32 v[98:99], v[174:175], v[98:99]
	v_pk_mul_f32 v[100:101], v[176:177], v[100:101]
	v_cvt_pk_bf16_f32 v98, v98, v99
	v_cvt_pk_bf16_f32 v99, v100, v101
	global_store_dwordx2 v190, v[98:99], s[94:95] offset:288
	s_add_i32 s97, s97, 1
	s_branch .Lx2_done
.Lx2_c1:
	s_add_u32 s94, s100, 0x10000
	s_addc_u32 s95, s101, 0
	v_pk_mul_f32 v[94:95], v[94:95], v[184:185] op_sel_hi:[1,0]
	v_pk_mul_f32 v[96:97], v[96:97], v[184:185] op_sel_hi:[1,0]
	v_pk_mul_f32 v[94:95], v[162:163], v[94:95]
	v_pk_mul_f32 v[96:97], v[164:165], v[96:97]
	v_cvt_pk_bf16_f32 v94, v94, v95
	v_cvt_pk_bf16_f32 v95, v96, v97
	global_store_dwordx2 v190, v[94:95], s[94:95]
	v_pk_mul_f32 v[90:91], v[90:91], v[184:185] op_sel_hi:[1,0]
	v_pk_mul_f32 v[92:93], v[92:93], v[184:185] op_sel_hi:[1,0]
	v_pk_mul_f32 v[90:91], v[166:167], v[90:91]
	v_pk_mul_f32 v[92:93], v[168:169], v[92:93]
	v_cvt_pk_bf16_f32 v90, v90, v91
	v_cvt_pk_bf16_f32 v91, v92, v93
	global_store_dwordx2 v190, v[90:91], s[94:95] offset:32
	v_pk_mul_f32 v[78:79], v[78:79], v[184:185] op_sel_hi:[1,0]
	v_pk_mul_f32 v[80:81], v[80:81], v[184:185] op_sel_hi:[1,0]
	v_pk_mul_f32 v[78:79], v[170:171], v[78:79]
	v_pk_mul_f32 v[80:81], v[172:173], v[80:81]
	v_cvt_pk_bf16_f32 v78, v78, v79
	v_cvt_pk_bf16_f32 v79, v80, v81
	global_store_dwordx2 v190, v[78:79], s[94:95] offset:256
	v_pk_mul_f32 v[74:75], v[74:75], v[184:185] op_sel_hi:[1,0]
	v_pk_mul_f32 v[76:77], v[76:77], v[184:185] op_sel_hi:[1,0]
	v_pk_mul_f32 v[74:75], v[174:175], v[74:75]
	v_pk_mul_f32 v[76:77], v[176:177], v[76:77]
	v_cvt_pk_bf16_f32 v74, v74, v75
	v_cvt_pk_bf16_f32 v75, v76, v77
	global_store_dwordx2 v190, v[74:75], s[94:95] offset:288
	s_add_u32 s94, s100, 0x18000
	s_addc_u32 s95, s101, 0
	v_pk_mul_f32 v[86:87], v[86:87], v[184:185] op_sel:[0,1] op_sel_hi:[1,1]
	v_pk_mul_f32 v[88:89], v[88:89], v[184:185] op_sel:[0,1] op_sel_hi:[1,1]
	v_pk_mul_f32 v[86:87], v[162:163], v[86:87]
	v_pk_mul_f32 v[88:89], v[164:165], v[88:89]
	v_cvt_pk_bf16_f32 v86, v86, v87
	v_cvt_pk_bf16_f32 v87, v88, v89
	global_store_dwordx2 v190, v[86:87], s[94:95]
	v_pk_mul_f32 v[82:83], v[82:83], v[184:185] op_sel:[0,1] op_sel_hi:[1,1]
	v_pk_mul_f32 v[84:85], v[84:85], v[184:185] op_sel:[0,1] op_sel_hi:[1,1]
	v_pk_mul_f32 v[82:83], v[166:167], v[82:83]
	v_pk_mul_f32 v[84:85], v[168:169], v[84:85]
	v_cvt_pk_bf16_f32 v82, v82, v83
	v_cvt_pk_bf16_f32 v83, v84, v85
	global_store_dwordx2 v190, v[82:83], s[94:95] offset:32
	v_pk_mul_f32 v[70:71], v[70:71], v[184:185] op_sel:[0,1] op_sel_hi:[1,1]
	v_pk_mul_f32 v[72:73], v[72:73], v[184:185] op_sel:[0,1] op_sel_hi:[1,1]
	v_pk_mul_f32 v[70:71], v[170:171], v[70:71]
	v_pk_mul_f32 v[72:73], v[172:173], v[72:73]
	v_cvt_pk_bf16_f32 v70, v70, v71
	v_cvt_pk_bf16_f32 v71, v72, v73
	global_store_dwordx2 v190, v[70:71], s[94:95] offset:256
	v_pk_mul_f32 v[66:67], v[66:67], v[184:185] op_sel:[0,1] op_sel_hi:[1,1]
	v_pk_mul_f32 v[68:69], v[68:69], v[184:185] op_sel:[0,1] op_sel_hi:[1,1]
	v_pk_mul_f32 v[66:67], v[174:175], v[66:67]
	v_pk_mul_f32 v[68:69], v[176:177], v[68:69]
	v_cvt_pk_bf16_f32 v66, v66, v67
	v_cvt_pk_bf16_f32 v67, v68, v69
	global_store_dwordx2 v190, v[66:67], s[94:95] offset:288
	s_add_i32 s97, s97, 1
	s_branch .Lx2_done
; DI unsigned pack2(float a, float b) { fv2 v = {a, b}; return __builtin_bit_cast(unsigned, __builtin_convertvector(v, bfv2)); }
; DI void rmsnorm_rows(const float* x, const float* g, bf16_t* outb, float* outf) {
;     ...
; #pragma unroll
;       for (int i = 0; i < 4; ++i) {
;         const float o0 = v[rr][i].x * rs * gg[i].x, o1 = v[rr][i].y * rs * gg[i].y, o2 = v[rr][i].z * rs * gg[i].z, o3 = v[rr][i].w * rs * gg[i].w;
;         if (outf) { *(float4*)(outf + (size_t)row * 1024 + lane * 4 + 256 * i) = make_float4(o0, o1, o2, o3); }
;         else { uint2 o; o.x = pack2(o0, o1); o.y = pack2(o2, o3); *(uint2*)(outb + (size_t)row * 1024 + lane * 4 + 256 * i) = o; }
.Lx2_c2:
	s_add_u32 s94, s100, 0x40000
	s_addc_u32 s95, s101, 0
	v_pk_mul_f32 v[150:151], v[150:151], v[186:187] op_sel_hi:[1,0]
	v_pk_mul_f32 v[152:153], v[152:153], v[186:187] op_sel_hi:[1,0]
	v_pk_mul_f32 v[150:151], v[162:163], v[150:151]
	v_pk_mul_f32 v[152:153], v[164:165], v[152:153]
	v_cvt_pk_bf16_f32 v150, v150, v151
	v_cvt_pk_bf16_f32 v151, v152, v153
	global_store_dwordx2 v190, v[150:151], s[94:95]
	v_pk_mul_f32 v[154:155], v[154:155], v[186:187] op_sel_hi:[1,0]
	v_pk_mul_f32 v[156:157], v[156:157], v[186:187] op_sel_hi:[1,0]
	v_pk_mul_f32 v[154:155], v[166:167], v[154:155]
	v_pk_mul_f32 v[156:157], v[168:169], v[156:157]
	v_cvt_pk_bf16_f32 v154, v154, v155
	v_cvt_pk_bf16_f32 v155, v156, v157
	global_store_dwordx2 v190, v[154:155], s[94:95] offset:32
	v_pk_mul_f32 v[192:193], v[192:193], v[186:187] op_sel_hi:[1,0]
	v_pk_mul_f32 v[194:195], v[194:195], v[186:187] op_sel_hi:[1,0]
	v_pk_mul_f32 v[192:193], v[170:171], v[192:193]
	v_pk_mul_f32 v[194:195], v[172:173], v[194:195]
	v_cvt_pk_bf16_f32 v192, v192, v193
	v_cvt_pk_bf16_f32 v193, v194, v195
	global_store_dwordx2 v190, v[192:193], s[94:95] offset:256
	v_pk_mul_f32 v[196:197], v[196:197], v[186:187] op_sel_hi:[1,0]
	v_pk_mul_f32 v[198:199], v[198:199], v[186:187] op_sel_hi:[1,0]
	v_pk_mul_f32 v[196:197], v[174:175], v[196:197]
	v_pk_mul_f32 v[198:199], v[176:177], v[198:199]
	v_cvt_pk_bf16_f32 v196, v196, v197
	v_cvt_pk_bf16_f32 v197, v198, v199
	global_store_dwordx2 v190, v[196:197], s[94:95] offset:288
	s_add_u32 s94, s100, 0x48000
	s_addc_u32 s95, s101, 0
	v_pk_mul_f32 v[158:159], v[158:159], v[186:187] op_sel:[0,1] op_sel_hi:[1,1]
	v_pk_mul_f32 v[160:161], v[160:161], v[186:187] op_sel:[0,1] op_sel_hi:[1,1]
	v_pk_mul_f32 v[158:159], v[162:163], v[158:159]
	v_pk_mul_f32 v[160:161], v[164:165], v[160:161]
	v_cvt_pk_bf16_f32 v158, v158, v159
	v_cvt_pk_bf16_f32 v159, v160, v161
	global_store_dwordx2 v190, v[158:159], s[94:95]
	v_pk_mul_f32 v[178:179], v[178:179], v[186:187] op_sel:[0,1] op_sel_hi:[1,1]
	v_pk_mul_f32 v[180:181], v[180:181], v[186:187] op_sel:[0,1] op_sel_hi:[1,1]
	v_pk_mul_f32 v[178:179], v[166:167], v[178:179]
	v_pk_mul_f32 v[180:181], v[168:169], v[180:181]
	v_cvt_pk_bf16_f32 v178, v178, v179
	v_cvt_pk_bf16_f32 v179, v180, v181
	global_store_dwordx2 v190, v[178:179], s[94:95] offset:32
	v_pk_mul_f32 v[210:211], v[210:211], v[186:187] op_sel:[0,1] op_sel_hi:[1,1]
	v_pk_mul_f32 v[212:213], v[212:213], v[186:187] op_sel:[0,1] op_sel_hi:[1,1]
	v_pk_mul_f32 v[210:211], v[170:171], v[210:211]
	v_pk_mul_f32 v[212:213], v[172:173], v[212:213]
	v_cvt_pk_bf16_f32 v210, v210, v211
	v_cvt_pk_bf16_f32 v211, v212, v213
	global_store_dwordx2 v190, v[210:211], s[94:95] offset:256
	v_pk_mul_f32 v[214:215], v[214:215], v[186:187] op_sel:[0,1] op_sel_hi:[1,1]
	v_pk_mul_f32 v[216:217], v[216:217], v[186:187] op_sel:[0,1] op_sel_hi:[1,1]
	v_pk_mul_f32 v[214:215], v[174:175], v[214:215]
	v_pk_mul_f32 v[216:217], v[176:177], v[216:217]
	v_cvt_pk_bf16_f32 v214, v214, v215
	v_cvt_pk_bf16_f32 v215, v216, v217
	global_store_dwordx2 v190, v[214:215], s[94:95] offset:288
	s_add_i32 s97, s97, 1
	s_branch .Lx2_done
.Lx2_c3:
	s_add_u32 s94, s100, 0x50000
	s_addc_u32 s95, s101, 0
	v_pk_mul_f32 v[218:219], v[218:219], v[188:189] op_sel_hi:[1,0]
	v_pk_mul_f32 v[220:221], v[220:221], v[188:189] op_sel_hi:[1,0]
	v_pk_mul_f32 v[218:219], v[162:163], v[218:219]
	v_pk_mul_f32 v[220:221], v[164:165], v[220:221]
	v_cvt_pk_bf16_f32 v218, v218, v219
	v_cvt_pk_bf16_f32 v219, v220, v221
	global_store_dwordx2 v190, v[218:219], s[94:95]
	v_pk_mul_f32 v[230:231], v[230:231], v[188:189] op_sel_hi:[1,0]
	v_pk_mul_f32 v[232:233], v[232:233], v[188:189] op_sel_hi:[1,0]
	v_pk_mul_f32 v[230:231], v[166:167], v[230:231]
	v_pk_mul_f32 v[232:233], v[168:169], v[232:233]
	v_cvt_pk_bf16_f32 v230, v230, v231
	v_cvt_pk_bf16_f32 v231, v232, v233
	global_store_dwordx2 v190, v[230:231], s[94:95] offset:32
	v_pk_mul_f32 v[134:135], v[134:135], v[188:189] op_sel_hi:[1,0]
	v_pk_mul_f32 v[136:137], v[136:137], v[188:189] op_sel_hi:[1,0]
	v_pk_mul_f32 v[134:135], v[170:171], v[134:135]
	v_pk_mul_f32 v[136:137], v[172:173], v[136:137]
	v_cvt_pk_bf16_f32 v134, v134, v135
	v_cvt_pk_bf16_f32 v135, v136, v137
	global_store_dwordx2 v190, v[134:135], s[94:95] offset:256
	v_pk_mul_f32 v[138:139], v[138:139], v[188:189] op_sel_hi:[1,0]
	v_pk_mul_f32 v[140:141], v[140:141], v[188:189] op_sel_hi:[1,0]
	v_pk_mul_f32 v[138:139], v[174:175], v[138:139]
	v_pk_mul_f32 v[140:141], v[176:177], v[140:141]
	v_cvt_pk_bf16_f32 v138, v138, v139
	v_cvt_pk_bf16_f32 v139, v140, v141
	global_store_dwordx2 v190, v[138:139], s[94:95] offset:288
	s_add_u32 s94, s100, 0x58000
	s_addc_u32 s95, s101, 0
	v_pk_mul_f32 v[234:235], v[234:235], v[188:189] op_sel:[0,1] op_sel_hi:[1,1]
	v_pk_mul_f32 v[236:237], v[236:237], v[188:189] op_sel:[0,1] op_sel_hi:[1,1]
	v_pk_mul_f32 v[234:235], v[162:163], v[234:235]
	v_pk_mul_f32 v[236:237], v[164:165], v[236:237]
	v_cvt_pk_bf16_f32 v234, v234, v235
	v_cvt_pk_bf16_f32 v235, v236, v237
	global_store_dwordx2 v190, v[234:235], s[94:95]
	v_pk_mul_f32 v[130:131], v[130:131], v[188:189] op_sel:[0,1] op_sel_hi:[1,1]
	v_pk_mul_f32 v[132:133], v[132:133], v[188:189] op_sel:[0,1] op_sel_hi:[1,1]
	v_pk_mul_f32 v[130:131], v[166:167], v[130:131]
	v_pk_mul_f32 v[132:133], v[168:169], v[132:133]
	v_cvt_pk_bf16_f32 v130, v130, v131
	v_cvt_pk_bf16_f32 v131, v132, v133
	global_store_dwordx2 v190, v[130:131], s[94:95] offset:32
	v_pk_mul_f32 v[142:143], v[142:143], v[188:189] op_sel:[0,1] op_sel_hi:[1,1]
	v_pk_mul_f32 v[144:145], v[144:145], v[188:189] op_sel:[0,1] op_sel_hi:[1,1]
	v_pk_mul_f32 v[142:143], v[170:171], v[142:143]
	v_pk_mul_f32 v[144:145], v[172:173], v[144:145]
	v_cvt_pk_bf16_f32 v142, v142, v143
	v_cvt_pk_bf16_f32 v143, v144, v145
	global_store_dwordx2 v190, v[142:143], s[94:95] offset:256
	v_pk_mul_f32 v[146:147], v[146:147], v[188:189] op_sel:[0,1] op_sel_hi:[1,1]
	v_pk_mul_f32 v[148:149], v[148:149], v[188:189] op_sel:[0,1] op_sel_hi:[1,1]
	v_pk_mul_f32 v[146:147], v[174:175], v[146:147]
	v_pk_mul_f32 v[148:149], v[176:177], v[148:149]
	v_cvt_pk_bf16_f32 v146, v146, v147
	v_cvt_pk_bf16_f32 v147, v148, v149
	global_store_dwordx2 v190, v[146:147], s[94:95] offset:288
	s_add_i32 s97, s97, 1
